# v21 + attention tile steps (DIFF, FOX): waves 4-7 start each step s_sleep 10/12 later than waves 0-3 so the two waves of a SIMD do not run their MFMA and VALU sections in lockstep (timing only)
# speedup vs baseline: 1.0003x; 1.0003x over previous
.LBB0_293:
	s_andn2_b64 vcc, exec, s[4:5]
	v_readlane_b32 s6, v255, 41
	v_readlane_b32 s7, v255, 42
	s_cbranch_vccnz .LBB0_884
	v_readfirstlane_b32 s98, v0
	s_nop 3
	s_lshr_b32 s98, s98, 8
	s_lshl_b32 s8, s6, 6
	v_and_b32_e32 v1, 63, v0
	v_or_b32_e32 v34, s8, v1
	v_readlane_b32 s40, v252, 19
	v_lshlrev_b64 v[2:3], 2, v[34:35]
	v_readlane_b32 s52, v252, 31
	v_readlane_b32 s53, v252, 32
	v_readlane_b32 s54, v252, 33
	v_readlane_b32 s55, v252, 34
	v_lshl_add_u64 v[4:5], s[52:53], 0, v[2:3]
	global_load_dword v1, v[4:5], off
	v_lshl_add_u64 v[4:5], s[54:55], 0, v[2:3]
	v_readlane_b32 s52, v252, 35
	v_readlane_b32 s53, v252, 36
	v_readlane_b32 s54, v252, 37
	v_readlane_b32 s55, v252, 38
	global_load_dword v6, v[4:5], off
	v_lshl_add_u64 v[4:5], s[52:53], 0, v[2:3]
	v_lshl_add_u64 v[2:3], s[54:55], 0, v[2:3]
	global_load_dword v4, v[4:5], off
	v_and_b32_e32 v5, 64, v217
	global_load_dword v2, v[2:3], off
	v_xor_b32_e32 v7, 1, v217
	v_add_u32_e32 v5, 64, v5
	v_cmp_lt_i32_e32 vcc, v7, v5
	v_xor_b32_e32 v8, 2, v217
	v_xor_b32_e32 v9, 4, v217
	v_cndmask_b32_e32 v7, v217, v7, vcc
	v_lshlrev_b32_e32 v7, 2, v7
	v_cmp_lt_i32_e32 vcc, v8, v5
	v_xor_b32_e32 v10, 8, v217
	s_lshl_b32 s92, s6, 7
	v_cndmask_b32_e32 v8, v217, v8, vcc
	v_lshlrev_b32_e32 v8, 2, v8
	v_cmp_lt_i32_e32 vcc, v9, v5
	v_readlane_b32 s56, v252, 39
	s_lshl_b64 s[4:5], s[92:93], 2
	v_cndmask_b32_e32 v9, v217, v9, vcc
	v_lshlrev_b32_e32 v9, 2, v9
	v_cmp_lt_i32_e32 vcc, v10, v5
	v_readlane_b32 s57, v252, 40
	v_cvt_f32_u32_e32 v3, s6
	v_cndmask_b32_e32 v10, v217, v10, vcc
	v_lshlrev_b32_e32 v10, 2, v10
	v_xor_b32_e32 v11, 16, v217
	s_mul_i32 s92, s6, 0x600
	s_add_u32 s6, s56, s4
	s_getreg_b32 s12, hwreg(HW_REG_XCC_ID, 0, 4)
	v_cmp_lt_i32_e32 vcc, v11, v5
	s_addc_u32 s7, s57, s5
	s_lshl_b64 s[10:11], s[92:93], 2
	v_writelane_b32 v255, s12, 43
	v_readlane_b32 s12, v253, 58
	v_cndmask_b32_e32 v11, v217, v11, vcc
	s_add_u32 s10, s12, s10
	v_xor_b32_e32 v12, 32, v217
	v_lshlrev_b32_e32 v11, 2, v11
	v_writelane_b32 v255, s10, 44
	v_readlane_b32 s10, v253, 59
	v_cmp_lt_i32_e32 vcc, v12, v5
	v_mul_f32_e32 v3, 0xbe99999a, v3
	s_addc_u32 s10, s10, s11
	v_cndmask_b32_e32 v5, v217, v12, vcc
	v_mul_f32_e32 v12, 0x3fb8aa3b, v3
	v_writelane_b32 v255, s10, 45
	s_mov_b32 s10, 0x3fb8aa3b
	v_rndne_f32_e32 v15, v12
	s_mov_b32 s9, s93
	v_readlane_b32 s44, v252, 23
	v_readlane_b32 s48, v252, 27
	v_lshlrev_b32_e32 v5, 2, v5
	s_lshl_b64 s[8:9], s[8:9], 2
	v_readlane_b32 s45, v252, 24
	v_readlane_b32 s49, v252, 28
	s_add_u32 s44, s48, s8
	v_readlane_b32 s46, v252, 25
	v_readlane_b32 s50, v252, 29
	s_addc_u32 s45, s49, s9
	v_readlane_b32 s47, v252, 26
	v_readlane_b32 s51, v252, 30
	s_add_u32 s46, s50, s8
	s_mov_b32 s8, 0xc2ce8ed0
	s_addc_u32 s47, s51, s9
	v_cmp_ngt_f32_e32 vcc, s8, v3
	s_mov_b32 s9, 0x42b17218
	v_readlane_b32 s66, v252, 49
	v_readlane_b32 s67, v252, 50
	s_mov_b32 s66, 0
	v_writelane_b32 v255, s86, 46
	v_readlane_b32 s41, v252, 20
	v_readlane_b32 s42, v252, 21
	v_readlane_b32 s43, v252, 22
	v_readlane_b32 s58, v252, 41
	v_readlane_b32 s59, v252, 42
	v_readlane_b32 s60, v252, 43
	v_readlane_b32 s61, v252, 44
	s_waitcnt vmcnt(0)
	v_mul_f32_e32 v13, v1, v6
	ds_bpermute_b32 v13, v7, v13
	v_readlane_b32 s62, v252, 45
	v_readlane_b32 s63, v252, 46
	v_readlane_b32 s64, v252, 47
	v_mul_f32_e32 v14, v4, v2
	ds_bpermute_b32 v7, v7, v14
	s_waitcnt lgkmcnt(1)
	v_fmac_f32_e32 v13, v1, v6
	ds_bpermute_b32 v1, v8, v13
	v_fma_f32 v14, v3, s10, -v12
	v_fmac_f32_e32 v14, 0x32a5705f, v3
	s_waitcnt lgkmcnt(1)
	v_fmac_f32_e32 v7, v4, v2
	ds_bpermute_b32 v2, v8, v7
	s_waitcnt lgkmcnt(1)
	v_add_f32_e32 v1, v13, v1
	ds_bpermute_b32 v6, v9, v1
	v_sub_f32_e32 v4, v12, v15
	v_add_f32_e32 v4, v4, v14
	s_waitcnt lgkmcnt(1)
	v_add_f32_e32 v2, v7, v2
	ds_bpermute_b32 v7, v9, v2
	s_waitcnt lgkmcnt(1)
	v_add_f32_e32 v1, v1, v6
	ds_bpermute_b32 v6, v10, v1
	v_cvt_i32_f32_e32 v8, v15
	v_exp_f32_e32 v4, v4
	s_waitcnt lgkmcnt(1)
	v_add_f32_e32 v2, v2, v7
	ds_bpermute_b32 v7, v10, v2
	s_waitcnt lgkmcnt(1)
	v_add_f32_e32 v1, v1, v6
	ds_bpermute_b32 v6, v11, v1
	v_ldexp_f32 v4, v4, v8
	v_cndmask_b32_e32 v4, 0, v4, vcc
	s_waitcnt lgkmcnt(1)
	v_add_f32_e32 v2, v2, v7
	ds_bpermute_b32 v7, v11, v2
	s_waitcnt lgkmcnt(1)
	v_add_f32_e32 v1, v1, v6
	ds_bpermute_b32 v6, v5, v1
	v_cmp_nlt_f32_e32 vcc, s9, v3
	v_mov_b32_e32 v10, 0x7f800000
	s_waitcnt lgkmcnt(1)
	v_add_f32_e32 v2, v2, v7
	ds_bpermute_b32 v5, v5, v2
	v_cndmask_b32_e32 v3, v10, v4, vcc
	v_mov_b32_e32 v4, 0x3f4ccccd
	s_waitcnt lgkmcnt(1)
	v_add_f32_e32 v1, v1, v6
	v_fmamk_f32 v3, v3, 0xbf19999a, v4
	s_waitcnt lgkmcnt(0)
	v_add_f32_e32 v2, v2, v5
	v_mul_f32_e32 v4, 0x3fb8aa3b, v1
	v_mul_f32_e32 v5, 0x3fb8aa3b, v2
	v_fma_f32 v6, v1, s10, -v4
	v_rndne_f32_e32 v7, v4
	v_fma_f32 v8, v2, s10, -v5
	v_rndne_f32_e32 v9, v5
	v_fmac_f32_e32 v6, 0x32a5705f, v1
	v_sub_f32_e32 v4, v4, v7
	v_fmac_f32_e32 v8, 0x32a5705f, v2
	v_sub_f32_e32 v5, v5, v9
	v_add_f32_e32 v4, v4, v6
	v_cvt_i32_f32_e32 v7, v7
	v_add_f32_e32 v5, v5, v8
	v_exp_f32_e32 v4, v4
	v_cvt_i32_f32_e32 v9, v9
	v_exp_f32_e32 v5, v5
	v_cmp_ngt_f32_e32 vcc, s8, v1
	v_ldexp_f32 v4, v4, v7
	v_sub_f32_e32 v184, 1.0, v3
	v_ldexp_f32 v5, v5, v9
	v_cndmask_b32_e32 v4, 0, v4, vcc
	v_cmp_ngt_f32_e32 vcc, s8, v2
	v_mov_b32_e32 v186, v184
	v_mov_b32_e32 v187, v184
	v_cndmask_b32_e32 v5, 0, v5, vcc
	v_cmp_nlt_f32_e32 vcc, s9, v1
	v_readlane_b32 s65, v252, 48
	s_nop 0
	v_cndmask_b32_e32 v1, v10, v4, vcc
	v_cmp_nlt_f32_e32 vcc, s9, v2
	s_nop 1
	v_cndmask_b32_e32 v2, v10, v5, vcc
	v_sub_f32_e32 v1, v1, v2
	v_add_f32_e32 v1, v3, v1
	s_nop 0
	v_readfirstlane_b32 s48, v1
	s_mov_b32 s49, s48
	s_mov_b32 s67, s48
	s_mov_b32 s68, s48
	s_mov_b32 s69, s48
	s_mov_b32 s70, s48
	s_mov_b32 s71, s48
	s_mov_b32 s72, s48
	s_mov_b32 s73, s48
	s_mov_b32 s74, s48
	s_mov_b32 s75, s48
	s_mov_b32 s76, s48
	s_mov_b32 s77, s48
	s_mov_b32 s78, s48
	s_mov_b32 s79, s48
	s_mov_b32 s80, s48
	s_branch .LBB0_296

.LBB0_322:
	s_cmp_lg_u32 s98, 0
	s_cbranch_scc0 .Lstg_diff
	s_sleep 10

.LBB0_485:
	s_cmp_lg_u32 s98, 0
	s_cbranch_scc0 .Lstg_fox_a
	s_sleep 12

.LBB0_497:
	s_waitcnt vmcnt(3)
	ds_write_b128 v170, v[132:135] offset:49152
	s_waitcnt vmcnt(2)
	ds_write_b128 v170, v[136:139] offset:57344
	s_waitcnt vmcnt(1)
	ds_write_b128 v171, v[140:143] offset:16384
	s_waitcnt vmcnt(0)
	ds_write_b128 v172, v[144:147] offset:16384
	s_and_saveexec_b64 s[4:5], s[38:39]
	v_mul_f32_e32 v68, 0xbfb8aa3b, v169
	ds_write_b32 v189, v68
	s_or_b64 exec, exec, s[4:5]
	s_cmp_gt_u32 s30, s24
	s_waitcnt lgkmcnt(0)
	s_barrier
	s_cmp_lg_u32 s98, 0
	s_cbranch_scc0 .Lstg_fox_b
	s_sleep 12
.Lstg_fox_b:
	s_cmp_gt_u32 s30, s24
	s_cbranch_scc0 .LBB0_502
	s_add_i32 s4, s30, 1
	s_cmp_lt_i32 s4, s25
	s_cbranch_scc0 .LBB0_505

	.amdhsa_kernel _Z8mega_fwd4Args
		.amdhsa_group_segment_fixed_size 0
		.amdhsa_private_segment_fixed_size 0
		.amdhsa_kernarg_size 464
		.amdhsa_user_sgpr_count 2
		.amdhsa_user_sgpr_dispatch_ptr 0
		.amdhsa_user_sgpr_queue_ptr 0
		.amdhsa_user_sgpr_kernarg_segment_ptr 1
		.amdhsa_user_sgpr_dispatch_id 0
		.amdhsa_user_sgpr_kernarg_preload_length 0
		.amdhsa_user_sgpr_kernarg_preload_offset 0
		.amdhsa_user_sgpr_private_segment_size 0
		.amdhsa_uses_dynamic_stack 0
		.amdhsa_enable_private_segment 0
		.amdhsa_system_sgpr_workgroup_id_x 1
		.amdhsa_system_sgpr_workgroup_id_y 0
		.amdhsa_system_sgpr_workgroup_id_z 0
		.amdhsa_system_sgpr_workgroup_info 0
		.amdhsa_system_vgpr_workitem_id 0
		.amdhsa_next_free_vgpr 256
		.amdhsa_next_free_sgpr 100
		.amdhsa_accum_offset 256
		.amdhsa_reserve_vcc 1
		.amdhsa_float_round_mode_32 0
		.amdhsa_float_round_mode_16_64 0
		.amdhsa_float_denorm_mode_32 3
		.amdhsa_float_denorm_mode_16_64 3
		.amdhsa_dx10_clamp 1
		.amdhsa_ieee_mode 1
		.amdhsa_fp16_overflow 0
		.amdhsa_tg_split 0
		.amdhsa_exception_fp_ieee_invalid_op 0
		.amdhsa_exception_fp_denorm_src 0
		.amdhsa_exception_fp_ieee_div_zero 0
		.amdhsa_exception_fp_ieee_overflow 0
		.amdhsa_exception_fp_ieee_underflow 0
		.amdhsa_exception_fp_ieee_inexact 0
		.amdhsa_exception_int_div_zero 0
	.end_amdhsa_kernel

amdhsa.kernels:
  - .agpr_count:     0
    .args:
      - .offset:         0
        .size:           208
        .value_kind:     by_value
      - .offset:         208
        .size:           4
        .value_kind:     hidden_block_count_x
      - .offset:         212
        .size:           4
        .value_kind:     hidden_block_count_y
      - .offset:         216
        .size:           4
        .value_kind:     hidden_block_count_z
      - .offset:         220
        .size:           2
        .value_kind:     hidden_group_size_x
      - .offset:         222
        .size:           2
        .value_kind:     hidden_group_size_y
      - .offset:         224
        .size:           2
        .value_kind:     hidden_group_size_z
      - .offset:         226
        .size:           2
        .value_kind:     hidden_remainder_x
      - .offset:         228
        .size:           2
        .value_kind:     hidden_remainder_y
      - .offset:         230
        .size:           2
        .value_kind:     hidden_remainder_z
      - .offset:         248
        .size:           8
        .value_kind:     hidden_global_offset_x
      - .offset:         256
        .size:           8
        .value_kind:     hidden_global_offset_y
      - .offset:         264
        .size:           8
        .value_kind:     hidden_global_offset_z
      - .offset:         272
        .size:           2
        .value_kind:     hidden_grid_dims
      - .offset:         328
        .size:           4
        .value_kind:     hidden_dynamic_lds_size
    .group_segment_fixed_size: 0
    .kernarg_segment_align: 8
    .kernarg_segment_size: 464
    .language:       OpenCL C
    .language_version:
      - 2
      - 0
    .max_flat_workgroup_size: 512
    .name:           _Z8mega_fwd4Args
    .private_segment_fixed_size: 0
    .sgpr_count:     106
    .sgpr_spill_count: 253
    .symbol:         _Z8mega_fwd4Args.kd
    .uniform_work_group_size: 1
    .uses_dynamic_stack: false
    .vgpr_count:     256
    .vgpr_spill_count: 0
    .wavefront_size: 64
